# prep phase: workgroups 256..511 start ~7us late (phase offset of the two workgroups of a CU), on top of mixer 10us stagger
# baseline (speedup 1.0000x reference)
.LBB0_175:
	s_or_b64 exec, exec, s[4:5]
	v_readlane_b32 s4, v254, 52
	v_readlane_b32 s5, v254, 53
	s_xor_b64 s[4:5], s[4:5], -1
	v_writelane_b32 v254, s4, 55
	s_mov_b32 s6, s58
	s_mov_b32 s7, s91
	v_writelane_b32 v254, s5, 56
	v_readlane_b32 s4, v253, 61
	v_readlane_b32 s5, v253, 62
	v_writelane_b32 v254, s6, 57
	s_andn2_b64 vcc, exec, s[4:5]
	s_mul_i32 s4, s6, 0x440
	v_writelane_b32 v254, s7, 58
	v_writelane_b32 v254, s4, 59
	s_barrier
	s_nop 0
	v_writelane_b32 v254, s5, 60
	s_cbranch_vccnz .LBB0_288
	v_readlane_b32 s4, v254, 59
	v_readlane_b32 s5, v254, 60
	s_mov_b32 s6, s4
	s_mov_b32 s5, s91
	v_writelane_b32 v254, s6, 59
	v_readlane_b32 s8, v253, 26
	v_readlane_b32 s18, v253, 36
	v_writelane_b32 v254, s7, 60
	s_lshl_b64 s[6:7], s[4:5], 2
	v_readlane_b32 s19, v253, 37
	s_add_u32 s4, s18, s6
	v_readlane_b32 s12, v253, 30
	v_readlane_b32 s13, v253, 31
	v_readlane_b32 s20, v253, 38
	s_addc_u32 s5, s19, s7
	v_readlane_b32 s16, v253, 34
	v_readlane_b32 s21, v253, 39
	s_add_u32 s6, s20, s6
	v_readlane_b32 s12, v254, 57
	v_readlane_b32 s9, v253, 27
	v_readlane_b32 s17, v253, 35
	s_addc_u32 s7, s21, s7
	s_lshl_b32 s16, s12, 9
	s_lshl_b32 s90, s12, 15
	s_or_b32 s17, s16, 0x100
	s_lshl_b64 s[8:9], s[90:91], 2
	v_readlane_b32 s48, v253, 42
	v_readlane_b32 s49, v253, 43
	s_add_u32 s8, s48, s8
	v_readlane_b32 s10, v253, 28
	v_readlane_b32 s11, v253, 29
	s_addc_u32 s9, s49, s9
	s_lshl_b32 s90, s12, 14
	v_readlane_b32 s52, v253, 46
	s_lshl_b64 s[10:11], s[90:91], 2
	v_readlane_b32 s22, v253, 40
	v_readlane_b32 s23, v253, 41
	v_readlane_b32 s53, v253, 47
	s_add_u32 s10, s52, s10
	v_readlane_b32 s23, v254, 54
	v_readlane_b32 s22, v253, 58
	s_movk_i32 s41, 0xff40
	s_movk_i32 s37, 0xff0
	s_addc_u32 s11, s53, s11
	s_lshl_b32 s18, s12, 8
	v_readlane_b32 s19, v254, 13
	v_readlane_b32 s14, v253, 32
	v_readlane_b32 s15, v253, 33
	v_readlane_b32 s13, v254, 58
	v_readlane_b32 s50, v253, 44
	v_readlane_b32 s51, v253, 45
	v_readlane_b32 s54, v253, 48
	v_readlane_b32 s55, v253, 49
	v_readlane_b32 s56, v253, 50
	v_readlane_b32 s57, v253, 51
	v_readlane_b32 s58, v253, 52
	v_readlane_b32 s59, v253, 53
	v_readlane_b32 s60, v253, 54
	v_readlane_b32 s61, v253, 55
	v_readlane_b32 s62, v253, 56
	v_readlane_b32 s63, v253, 57
	v_readlane_b32 s20, v254, 13
	s_cmpk_lt_u32 s20, 0x100
	s_cbranch_scc1 .Ldp_nodelay
	s_sleep 127
	s_sleep 127
.Ldp_nodelay:
.LBB0_177:
	v_mov_b32_e32 v0, v179
	s_lshl_b32 s20, s19, 4
	v_mul_hi_i32 v1, v0, s66
	v_lshrrev_b32_e32 v2, 31, v1
	v_ashrrev_i32_e32 v1, 5, v1
	v_add_u32_e32 v1, v1, v2
	v_mad_u64_u32 v[2:3], s[12:13], v1, s41, v[0:1]
	v_add_u32_e32 v3, s20, v1
	s_waitcnt vmcnt(1)
	v_mov_b64_e32 v[4:5], s[78:79]
	v_mad_i64_i32 v[4:5], s[12:13], v3, s67, v[4:5]
	v_ashrrev_i32_e32 v3, 31, v2
	v_lshl_add_u64 v[4:5], v[2:3], 1, v[4:5]
	v_add_co_u32_e32 v6, vcc, 0x1000, v4
	s_cmpk_lt_i32 s19, 0x800
	s_nop 0
	v_addc_co_u32_e32 v7, vcc, 0, v5, vcc
	global_load_ushort v8, v[6:7], off offset:2048
	s_cselect_b64 s[12:13], -1, 0
	s_and_b64 s[14:15], s[12:13], exec
	s_cselect_b32 s14, s37, 0x7f0
	s_and_b32 s21, s14, s20
	s_waitcnt vmcnt(1)
	v_add_u32_e32 v9, s21, v1
	v_lshl_add_u64 v[6:7], v[4:5], 0, s[26:27]
	v_cmp_lt_i32_e32 vcc, 0, v9
	v_mov_b32_e32 v5, 0
	v_mov_b32_e32 v4, 0
	s_and_saveexec_b64 s[14:15], vcc
	s_cbranch_execz .LBB0_179
	v_add_co_u32_e32 v10, vcc, 0xfffff000, v6
	s_nop 1
	v_addc_co_u32_e32 v11, vcc, -1, v7, vcc
	global_load_ushort v4, v[10:11], off offset:-2688
	s_waitcnt vmcnt(0)
	v_lshlrev_b32_e32 v4, 16, v4
